# P5 selected-block attention: V^T fragment reads of group g+1 requested before the two PV MFMAs of group g (second register set v238-245); stack: g2, P9 waits, g3 ladder, rownorm ladders
# speedup vs baseline: 1.0123x; 1.0123x over previous
.LBB0_1806:
	v_add_u32_e32 v16, v230, v229
	ds_read_b64_tr_b16 v[22:23], v16 offset:18432
	ds_read_b64_tr_b16 v[24:25], v16 offset:19584
	ds_read_b64_tr_b16 v[26:27], v16 offset:18496
	ds_read_b64_tr_b16 v[28:29], v16 offset:19648
	ds_read_b64_tr_b16 v[238:239], v16 offset:20736
	ds_read_b64_tr_b16 v[240:241], v16 offset:21888
	ds_read_b64_tr_b16 v[242:243], v16 offset:20800
	ds_read_b64_tr_b16 v[244:245], v16 offset:21952
	v_add_f32_e32 v18, v15, v18
	v_cvt_pk_bf16_f32 v12, v98, v99
	v_cvt_pk_bf16_f32 v13, v100, v101
	v_cvt_pk_bf16_f32 v14, v102, v103
	v_cvt_pk_bf16_f32 v15, v104, v105
	v_mov_b64_e32 v[82:83], v[130:131]
	v_mov_b64_e32 v[84:85], v[132:133]
	s_waitcnt lgkmcnt(6)
	v_mfma_f32_32x32x16_bf16 v[50:65], v[22:25], v[12:15], v[50:65]
	v_mov_b64_e32 v[86:87], v[134:135]
	v_mov_b64_e32 v[88:89], v[136:137]
	v_mov_b64_e32 v[90:91], v[138:139]
	v_mov_b64_e32 v[92:93], v[140:141]
	v_mov_b64_e32 v[94:95], v[142:143]
	v_mov_b64_e32 v[96:97], v[144:145]
	s_waitcnt lgkmcnt(4)
	v_mfma_f32_32x32x16_bf16 v[34:49], v[26:29], v[12:15], v[34:49]
	ds_read_b64_tr_b16 v[22:23], v16 offset:23040
	ds_read_b64_tr_b16 v[24:25], v16 offset:24192
	ds_read_b64_tr_b16 v[26:27], v16 offset:23104
	ds_read_b64_tr_b16 v[28:29], v16 offset:24256
	v_cvt_pk_bf16_f32 v12, v106, v107
	v_cvt_pk_bf16_f32 v13, v108, v109
	v_cvt_pk_bf16_f32 v14, v110, v111
	v_cvt_pk_bf16_f32 v15, v112, v113
	s_waitcnt lgkmcnt(6)
	s_nop 0
	v_mfma_f32_32x32x16_bf16 v[50:65], v[238:241], v[12:15], v[50:65]
	s_waitcnt lgkmcnt(4)
	v_mfma_f32_32x32x16_bf16 v[34:49], v[242:245], v[12:15], v[34:49]
	ds_read_b64_tr_b16 v[238:239], v16 offset:25344
	ds_read_b64_tr_b16 v[240:241], v16 offset:26496
	ds_read_b64_tr_b16 v[242:243], v16 offset:25408
	ds_read_b64_tr_b16 v[244:245], v16 offset:26560
	v_cvt_pk_bf16_f32 v12, v114, v115
	v_cvt_pk_bf16_f32 v13, v116, v117
	v_cvt_pk_bf16_f32 v14, v118, v119
	v_cvt_pk_bf16_f32 v15, v120, v121
	s_waitcnt lgkmcnt(6)
	s_nop 0
	v_mfma_f32_32x32x16_bf16 v[50:65], v[22:25], v[12:15], v[50:65]
	s_waitcnt lgkmcnt(4)
	v_mfma_f32_32x32x16_bf16 v[34:49], v[26:29], v[12:15], v[34:49]
	v_cvt_pk_bf16_f32 v12, v122, v123
	v_cvt_pk_bf16_f32 v13, v124, v125
	v_cvt_pk_bf16_f32 v14, v126, v127
	v_cvt_pk_bf16_f32 v15, v128, v129
	s_waitcnt lgkmcnt(2)
	s_nop 0
	v_mfma_f32_32x32x16_bf16 v[50:65], v[238:241], v[12:15], v[50:65]
	s_waitcnt lgkmcnt(0)
	v_mfma_f32_32x32x16_bf16 v[34:49], v[242:245], v[12:15], v[34:49]

.LBB0_1812:
	v_add_u32_e32 v2, v230, v229
	ds_read_b64_tr_b16 v[22:23], v2 offset:27648
	ds_read_b64_tr_b16 v[24:25], v2 offset:28800
	ds_read_b64_tr_b16 v[26:27], v2 offset:27712
	ds_read_b64_tr_b16 v[28:29], v2 offset:28864
	ds_read_b64_tr_b16 v[238:239], v2 offset:29952
	ds_read_b64_tr_b16 v[240:241], v2 offset:31104
	ds_read_b64_tr_b16 v[242:243], v2 offset:30016
	ds_read_b64_tr_b16 v[244:245], v2 offset:31168
	v_add_f32_e32 v18, v15, v18
	v_cvt_pk_bf16_f32 v12, v66, v67
	v_cvt_pk_bf16_f32 v13, v68, v69
	v_cvt_pk_bf16_f32 v14, v70, v71
	v_cvt_pk_bf16_f32 v15, v72, v73
	v_mov_b64_e32 v[114:115], v[130:131]
	v_mov_b64_e32 v[116:117], v[132:133]
	s_waitcnt lgkmcnt(6)
	v_mfma_f32_32x32x16_bf16 v[50:65], v[22:25], v[12:15], v[50:65]
	v_mov_b64_e32 v[118:119], v[134:135]
	v_mov_b64_e32 v[120:121], v[136:137]
	v_mov_b64_e32 v[122:123], v[138:139]
	v_mov_b64_e32 v[124:125], v[140:141]
	v_mov_b64_e32 v[126:127], v[142:143]
	v_mov_b64_e32 v[128:129], v[144:145]
	s_waitcnt lgkmcnt(4)
	v_mfma_f32_32x32x16_bf16 v[34:49], v[26:29], v[12:15], v[34:49]
	ds_read_b64_tr_b16 v[22:23], v2 offset:32256
	ds_read_b64_tr_b16 v[24:25], v2 offset:33408
	ds_read_b64_tr_b16 v[26:27], v2 offset:32320
	ds_read_b64_tr_b16 v[28:29], v2 offset:33472
	v_cvt_pk_bf16_f32 v12, v74, v75
	v_cvt_pk_bf16_f32 v13, v76, v77
	v_cvt_pk_bf16_f32 v14, v78, v79
	v_cvt_pk_bf16_f32 v15, v80, v81
	s_waitcnt lgkmcnt(6)
	s_nop 0
	v_mfma_f32_32x32x16_bf16 v[50:65], v[238:241], v[12:15], v[50:65]
	s_waitcnt lgkmcnt(4)
	v_mfma_f32_32x32x16_bf16 v[34:49], v[242:245], v[12:15], v[34:49]
	ds_read_b64_tr_b16 v[238:239], v2 offset:34560
	ds_read_b64_tr_b16 v[240:241], v2 offset:35712
	ds_read_b64_tr_b16 v[242:243], v2 offset:34624
	ds_read_b64_tr_b16 v[244:245], v2 offset:35776
	v_cvt_pk_bf16_f32 v12, v82, v83
	v_cvt_pk_bf16_f32 v13, v84, v85
	v_cvt_pk_bf16_f32 v14, v86, v87
	v_cvt_pk_bf16_f32 v15, v88, v89
	s_waitcnt lgkmcnt(6)
	s_nop 0
	v_mfma_f32_32x32x16_bf16 v[50:65], v[22:25], v[12:15], v[50:65]
	s_waitcnt lgkmcnt(4)
	v_mfma_f32_32x32x16_bf16 v[34:49], v[26:29], v[12:15], v[34:49]
	v_cvt_pk_bf16_f32 v12, v90, v91
	v_cvt_pk_bf16_f32 v13, v92, v93
	v_cvt_pk_bf16_f32 v14, v94, v95
	v_cvt_pk_bf16_f32 v15, v96, v97
	s_waitcnt lgkmcnt(2)
	s_nop 0
	v_mfma_f32_32x32x16_bf16 v[50:65], v[238:241], v[12:15], v[50:65]
	s_waitcnt lgkmcnt(0)
	v_mfma_f32_32x32x16_bf16 v[34:49], v[242:245], v[12:15], v[34:49]
